# P3 attention/pooling units run on the workgroups that consume their rows in P4 (same XCC, run-time checked); P3->P4 seam becomes a group-local synchronisation
# speedup vs baseline: 1.0130x; 1.0039x over previous
; #define LAS __attribute__((address_space(3)))
; __device__ __forceinline__ bool attn_unit(const Ptrs& P, LAS unsigned char* lds, int unit, int tid, int wave, int lane, bool pre, int nxt) {
;     const int n = unit & 31, kh = (unit >> 5) & 3, b = unit >> 7;
;     const int g = wave & 3, q0 = 64 * (wave >> 2), h = kh * 4 + g, r = lane & 31, hh = lane >> 5;
;     unsigned char* ws = P.ws;
;     bf16_t* Qb = (bf16_t*)(ws + WS_Q) + (size_t)(b * SEQ + n * 128 + q0) * DM + h * 64;
;     const bf16_t* Kg = (const bf16_t*)(ws + WS_K) + (size_t)b * SEQ * KVW + kh * 64; const bf16_t* Vg = (const bf16_t*)(ws + WS_VT) + (size_t)(b * 4 + kh) * 64 * SEQ;
;     const bf16_t* Kcg = (const bf16_t*)(ws + WS_KC) + (size_t)b * CTX * KVW + kh * 64; const bf16_t* Vcg = (const bf16_t*)(ws + WS_VCT) + (size_t)(b * 4 + kh) * 64 * CTX;
;     float mq = fabsf(P.qg[lane]), mk = fabsf(P.kg[lane]);
; #pragma unroll
;     for (int o = 1; o < 64; o <<= 1) { mq = fmaxf(mq, __shfl_xor(mq, o)); mk = fmaxf(mk, __shfl_xor(mk, o)); }
;     const float sink2 = P.sink[h] * LOG2E; const float mshift = fmaxf(64.0f * QSCALE * mq * mk, sink2);
;     bf16x8_t qf[2][4];
; #pragma unroll
;     for (int cb = 0; cb < 2; ++cb)
; #pragma unroll
;         for (int ds = 0; ds < 4; ++ds) qf[cb][ds] = __builtin_nontemporal_load((const bf16x8_t*)(Qb + (size_t)(32 * cb + r) * DM + 16 * ds + 8 * hh));
;     f32x16 o[2][2];
; #pragma unroll
;     for (int db = 0; db < 2; ++db)
; #pragma unroll
;         for (int cb = 0; cb < 2; ++cb)
; #pragma unroll
;             for (int i = 0; i < 16; ++i) o[db][cb][i] = 0.f;
;     float rs[2] = {0.f, 0.f};
;     f32x16 negm;
; #pragma unroll
;     for (int i = 0; i < 16; ++i) negm[i] = -mshift;
; __device__ __forceinline__ void mk_p3(const Ptrs& P, LAS unsigned char* lds, int tid, int wave, int lane, int bx, int G, bool dry) {
;     ...
;         { bool pre = false; for (int u = bx; u < NB * 32 * 4; u += G) pre = attn_unit(P, lds, u, tid, wave, lane, pre, u + G < NB * 32 * 4 ? u + G : -1); }
.LBB9_305:
	s_cmp_lt_i32 s92, 4
	s_cselect_b64 s[2:3], -1, 0
	s_and_b64 s[22:23], s[2:3], s[0:1]
	s_andn2_b64 vcc, exec, s[22:23]
	s_cbranch_vccnz .LBB9_444
	v_writelane_b32 v251, s22, 33
	s_cmpk_gt_i32 s97, 0x1ff
	v_and_b32_e32 v171, 31, v208
	v_writelane_b32 v251, s23, 34
	v_writelane_b32 v251, s80, 35
	v_lshrrev_b32_e32 v184, 5, v170
	s_nop 0
	v_writelane_b32 v251, s81, 36
	v_writelane_b32 v251, s96, 37
	v_writelane_b32 v251, s83, 38
	v_writelane_b32 v251, s97, 39
	s_cbranch_scc1 .LBB9_413
	v_mbcnt_lo_u32_b32 v0, -1, 0
	v_mbcnt_hi_u32_b32 v0, -1, v0
	v_and_b32_e32 v1, 64, v0
	v_add_u32_e32 v1, 64, v1
	v_xor_b32_e32 v2, 1, v0
	v_cmp_lt_i32_e32 vcc, v2, v1
	s_bfe_u32 s0, s40, 0x20006
	v_writelane_b32 v251, s0, 40
	v_cndmask_b32_e32 v2, v0, v2, vcc
	v_lshlrev_b32_e32 v185, 2, v2
	v_xor_b32_e32 v2, 2, v0
	v_cmp_lt_i32_e32 vcc, v2, v1
	s_lshl_b32 s0, s50, 4
	s_and_b32 s33, s0, 0x3fffffc0
	v_cndmask_b32_e32 v2, v0, v2, vcc
	v_lshlrev_b32_e32 v186, 2, v2
	v_xor_b32_e32 v2, 4, v0
	v_cmp_lt_i32_e32 vcc, v2, v1
	s_cmpk_lt_u32 s40, 0x8c0
	s_cselect_b64 s[54:55], -1, 0
	v_cndmask_b32_e32 v2, v0, v2, vcc
	v_lshlrev_b32_e32 v187, 2, v2
	v_xor_b32_e32 v2, 8, v0
	v_cmp_lt_i32_e32 vcc, v2, v1
	s_or_b32 s2, s0, 63
	s_or_b32 s3, s33, 32
	v_cndmask_b32_e32 v2, v0, v2, vcc
	v_lshlrev_b32_e32 v188, 2, v2
	v_xor_b32_e32 v2, 16, v0
	v_cmp_lt_i32_e32 vcc, v2, v1
	v_or_b32_e32 v5, 32, v170
	v_lshlrev_b32_e32 v191, 4, v184
	v_cndmask_b32_e32 v2, v0, v2, vcc
	v_lshlrev_b32_e32 v189, 2, v2
	v_xor_b32_e32 v2, 32, v0
	v_cmp_lt_i32_e32 vcc, v2, v1
	v_mov_b32_e32 v1, 0
	v_mul_u32_u24_e32 v6, 0x110, v5
	v_cndmask_b32_e32 v0, v0, v2, vcc
	v_lshlrev_b32_e32 v190, 2, v0
	v_lshlrev_b32_e32 v0, 2, v184
	v_sub_u32_e32 v0, v171, v0
	v_cmp_lt_i32_e64 s[36:37], 10, v0
	v_cmp_gt_i32_e64 s[0:1], 1, v0
	v_cmp_gt_i32_e64 s[4:5], 2, v0
	v_writelane_b32 v251, s36, 41
	v_cmp_gt_i32_e64 s[6:7], 3, v0
	v_cmp_gt_i32_e64 s[8:9], 4, v0
	v_writelane_b32 v251, s37, 42
	v_cmp_lt_i32_e64 s[36:37], 15, v0
	v_cmp_gt_i32_e64 s[10:11], 9, v0
	v_cmp_gt_i32_e64 s[12:13], 10, v0
	v_writelane_b32 v251, s36, 43
	v_cmp_gt_i32_e64 s[14:15], 11, v0
	v_cmp_gt_i32_e64 s[16:17], 12, v0
	v_writelane_b32 v251, s37, 44
	v_cmp_lt_i32_e64 s[36:37], 16, v0
	v_cmp_gt_i32_e64 s[18:19], 17, v0
	v_cmp_gt_i32_e64 s[20:21], 18, v0
	v_writelane_b32 v251, s36, 45
	v_cmp_gt_i32_e64 s[22:23], 19, v0
	v_cmp_gt_i32_e64 s[24:25], 20, v0
	v_writelane_b32 v251, s37, 46
	v_cmp_lt_i32_e64 s[36:37], 17, v0
	v_cmp_gt_i32_e64 s[26:27], 25, v0
	v_cmp_gt_i32_e64 s[28:29], 26, v0
	v_writelane_b32 v251, s36, 47
	v_cmp_gt_i32_e64 s[30:31], 27, v0
	v_cmp_gt_i32_e64 s[34:35], 28, v0
	v_writelane_b32 v251, s37, 48
	v_cmp_lt_i32_e64 s[36:37], 18, v0
	v_cmp_lt_i32_e64 s[56:57], -1, v0
	v_cmp_lt_i32_e64 s[86:87], 0, v0
	v_writelane_b32 v251, s36, 49
	v_cmp_lt_i32_e64 s[60:61], 1, v0
	v_cmp_lt_i32_e64 s[62:63], 2, v0
	v_writelane_b32 v251, s37, 50
	v_cmp_lt_i32_e64 s[36:37], 23, v0
	v_cmp_lt_i32_e64 s[64:65], 7, v0
	v_cmp_lt_i32_e64 s[66:67], 8, v0
	v_writelane_b32 v251, s36, 51
	v_cmp_lt_i32_e64 s[72:73], 9, v0
	v_lshlrev_b32_e32 v4, 3, v184
	v_writelane_b32 v251, s37, 52
	v_cmp_lt_i32_e64 s[36:37], 24, v0
	v_mul_u32_u24_e32 v3, 0x110, v171
	v_lshlrev_b32_e32 v2, 10, v171
	v_writelane_b32 v251, s36, 53
	s_movk_i32 s52, 0x110
	v_add3_u32 v3, v3, v191, 0
	v_writelane_b32 v251, s37, 54
	v_cmp_lt_i32_e64 s[36:37], 25, v0
	v_lshlrev_b32_e32 v176, 1, v4
	s_mov_b32 s77, 0
	v_writelane_b32 v251, s36, 55
	v_add_u32_e32 v195, 0x4800, v3
	v_add_u32_e32 v198, 0xd400, v3
	v_writelane_b32 v251, s37, 56
	v_cmp_lt_i32_e64 s[36:37], 26, v0
	v_lshlrev_b32_e32 v0, 2, v170
	v_mad_u32_u24 v200, v5, s52, 0
	v_writelane_b32 v251, s36, 57
	v_mad_u32_u24 v201, v171, s52, 0
	s_mov_b64 s[68:69], 0
	v_writelane_b32 v251, s37, 58
	s_add_u32 s36, s90, 0x6200000
	v_writelane_b32 v251, s36, 59
	s_addc_u32 s36, s91, 0
	v_writelane_b32 v251, s36, 60
	s_add_u32 s36, s90, 0x7200000
	v_writelane_b32 v251, s36, 61
	s_addc_u32 s36, s91, 0
	v_writelane_b32 v251, s36, 62
	v_mov_b32_e32 v178, v176
	v_readlane_b32 s36, v251, 16
	s_add_u32 s36, s90, 0x4200000
	v_readlane_b32 s37, v251, 17
	v_readlane_b32 s38, v251, 18
	v_readlane_b32 s39, v251, 19
	v_readlane_b32 s40, v251, 20
	v_readlane_b32 s41, v251, 21
	v_readlane_b32 s42, v251, 22
	v_readlane_b32 s43, v251, 23
	v_readlane_b32 s44, v251, 24
	v_readlane_b32 s45, v251, 25
	v_readlane_b32 s46, v251, 26
	v_readlane_b32 s47, v251, 27
	v_readlane_b32 s48, v251, 28
	v_readlane_b32 s49, v251, 29
	v_readlane_b32 s50, v251, 30
	v_readlane_b32 s51, v251, 31
	v_writelane_b32 v251, s36, 63
	s_addc_u32 s36, s91, 0
	v_writelane_b32 v250, s36, 0
	s_add_u32 s36, s90, 0x6a00000
	v_writelane_b32 v250, s36, 1
	s_addc_u32 s36, s91, 0
	v_writelane_b32 v250, s36, 2
	s_add_u32 s36, s90, 0x7280000
	v_writelane_b32 v250, s36, 3
	s_addc_u32 s36, s91, 0
	v_writelane_b32 v250, s36, 4
	s_add_u32 s36, s90, 0x2000000
	v_writelane_b32 v250, s36, 5
	s_addc_u32 s36, s91, 0
	v_lshl_add_u64 v[172:173], s[40:41], 0, v[0:1]
	v_writelane_b32 v250, s36, 6
	s_add_i32 s40, 0, 0x11800
	s_add_i32 s76, 0, 0x16000
	v_writelane_b32 v250, s40, 7
	v_writelane_b32 v250, s76, 8
	v_writelane_b32 v250, s88, 9
	v_lshl_add_u64 v[174:175], s[42:43], 0, v[0:1]
	v_readlane_b32 s36, v251, 32
	v_writelane_b32 v250, s89, 10
	v_writelane_b32 v250, s90, 11
	v_writelane_b32 v250, s91, 12
	v_add3_u32 v0, v6, v191, 0
	v_mul_u32_u24_e32 v6, 0x90, v171
	v_writelane_b32 v250, s92, 13
	v_lshl_or_b32 v192, s36, 6, v170
	s_movk_i32 s37, 0x90
	v_add3_u32 v196, v6, v191, 0
	v_writelane_b32 v250, s93, 14
	v_add_u32_e32 v193, 0xfffffb80, v192
	v_add_u32_e32 v194, 0x4800, v0
	v_add_u32_e32 v197, 0xd400, v0
	v_add_u32_e32 v199, 0x8c00, v196
	v_mad_u32_u24 v202, v171, s37, 0
	v_mov_b32_e32 v179, v1
	v_lshlrev_b32_e32 v180, 1, v2
	v_mov_b32_e32 v181, v1
	s_mov_b32 s36, 0xf0f0f0f1
	s_movk_i32 s37, 0xffef
	s_movk_i32 s38, 0x490
	s_mov_b32 s39, 0x38e38e39
	v_readlane_b32 s42, v251, 39
	v_writelane_b32 v250, s94, 22
	v_writelane_b32 v250, s94, 23
	v_mov_b32_e32 v254, 0x24008
	ds_read_b32 v254, v254
	s_waitcnt lgkmcnt(0)
	v_readfirstlane_b32 s98, v254
	s_nop 3
	s_cmp_eq_u32 s98, 1
	s_cbranch_scc0 .Lrm_a
	s_cmpk_lg_i32 s94, 0x100
	s_cbranch_scc1 .Lrm_a
	s_and_b32 s98, s42, 7
	s_lshl_b32 s98, s98, 3
	s_bfe_u32 s99, s42, 0x30003
	s_or_b32 s98, s98, s99
	s_lshr_b32 s99, s42, 6
	s_lshl_b32 s99, s99, 5
	s_lshr_b32 s42, s98, 4
	s_lshl_b32 s42, s42, 7
	s_or_b32 s42, s42, s99
	s_and_b32 s98, s98, 15
	s_lshl_b32 s98, s98, 1
	s_or_b32 s42, s42, s98
	s_mov_b32 s98, 1
	s_movk_i32 s99, 0x400
	v_writelane_b32 v250, s98, 22
	v_writelane_b32 v250, s99, 23

; __device__ __forceinline__ unsigned cvtpk(float lo, float hi) { f32x2_t v = {lo, hi}; bf16x2_t b = __builtin_convertvector(v, bf16x2_t); return __builtin_bit_cast(unsigned, b); }
; #define LAS __attribute__((address_space(3)))
; __device__ __forceinline__ bool attn_unit(const Ptrs& P, LAS unsigned char* lds, int unit, int tid, int wave, int lane, bool pre, int nxt) {
;     ...
;         for (int kt = 0; kt < 4; ++kt) {
;             if (c == 0 && 32 * kt + 31 < q0) continue;
;             if (c == 2 && 32 * kt > q0 + 63) continue;
;             bf16x8_t kf[4], vf[2][2];
; #pragma unroll
;             for (int ds = 0; ds < 4; ++ds) kf[ds] = *(const LAS bf16x8_t*)(Kl + (32 * kt + r) * AT_KP + (16 * ds + 8 * hh) * 2);
; #pragma unroll
;             for (int db = 0; db < 2; ++db)
; #pragma unroll
;                 for (int s = 0; s < 2; ++s) vf[db][s] = *(const LAS bf16x8_t*)(Vl + (32 * db + r) * AT_VP + (32 * kt + 16 * s + 8 * hh) * 2);
; #pragma unroll
;             for (int cb = 0; cb < 2; ++cb) {
;                 const int dq = 32 * kt - (q0 + 32 * cb);
;                 if ((c == 0 && dq < 0) || (c == 2 && dq > 0)) continue;
;                 const bool diag = (c == 0 || c == 2) && dq == 0;
;                 f32x16 st = MFMA32(kf[0], qf[cb][0], negm);
;                 st = MFMA32(kf[1], qf[cb][1], st); st = MFMA32(kf[2], qf[cb][2], st); st = MFMA32(kf[3], qf[cb][3], st);
;                 float p[16];
; #pragma unroll
;                 for (int i = 0; i < 16; ++i) p[i] = __builtin_amdgcn_exp2f(st[i]);
;                 if (diag) {
;                     const int thr = r - 4 * hh;
; #pragma unroll
;                     for (int i = 0; i < 16; ++i) { const bool vis = c == 0 ? crow(i, 0) >= thr : crow(i, 0) <= thr; p[i] = vis ? p[i] : 0.f; }
;                 }
;                 float s4 = 0.f;
; #pragma unroll
;                 for (int i = 0; i < 16; ++i) s4 += p[i];
;                 rs[cb] += s4;
; #pragma unroll
;                 for (int s = 0; s < 2; ++s) {
;                     u32x4 w; w.x = cvtpk(p[8 * s], p[8 * s + 1]); w.y = cvtpk(p[8 * s + 2], p[8 * s + 3]); w.z = cvtpk(p[8 * s + 4], p[8 * s + 5]); w.w = cvtpk(p[8 * s + 6], p[8 * s + 7]);
;                     const bf16x8_t pb = __builtin_bit_cast(bf16x8_t, w);
;                     o[0][cb] = MFMA32(vf[0][s], pb, o[0][cb]); o[1][cb] = MFMA32(vf[1][s], pb, o[1][cb]);
;                 }
.LBB9_400:
	ds_read_b128 v[238:241], v196 offset:0
	ds_read_b128 v[242:245], v196 offset:32
	ds_read_b128 v[246:249], v196 offset:64
	ds_read_b128 v[204:207], v196 offset:96
	s_waitcnt lgkmcnt(0)
	v_mfma_f32_32x32x16_bf16 v[82:97], v[238:241], v[114:117], v[18:33]
	v_mfma_f32_32x32x16_bf16 v[82:97], v[242:245], v[118:121], v[82:97]
	v_mfma_f32_32x32x16_bf16 v[82:97], v[246:249], v[122:125], v[82:97]
	v_mfma_f32_32x32x16_bf16 v[82:97], v[204:207], v[126:129], v[82:97]
	v_mfma_f32_32x32x16_bf16 v[98:113], v[238:241], v[130:133], v[18:33]
	v_mfma_f32_32x32x16_bf16 v[98:113], v[242:245], v[134:137], v[98:113]
	v_mfma_f32_32x32x16_bf16 v[98:113], v[246:249], v[138:141], v[98:113]
	v_mfma_f32_32x32x16_bf16 v[98:113], v[204:207], v[142:145], v[98:113]
	ds_read_b128 v[146:149], v195 offset:0
	ds_read_b128 v[150:153], v195 offset:32
	ds_read_b128 v[154:157], v194 offset:0
	ds_read_b128 v[158:161], v194 offset:32
	ds_read_b128 v[238:241], v196 offset:4608
	ds_read_b128 v[242:245], v196 offset:4640
	ds_read_b128 v[246:249], v196 offset:4672
	ds_read_b128 v[204:207], v196 offset:4704
	v_exp_f32_e32 v82, v82
	v_exp_f32_e32 v83, v83
	v_exp_f32_e32 v84, v84
	v_exp_f32_e32 v85, v85
	v_exp_f32_e32 v86, v86
	v_exp_f32_e32 v87, v87
	v_exp_f32_e32 v88, v88
	v_exp_f32_e32 v89, v89
	v_exp_f32_e32 v90, v90
	v_exp_f32_e32 v91, v91
	v_exp_f32_e32 v92, v92
	v_exp_f32_e32 v93, v93
	v_exp_f32_e32 v94, v94
	v_exp_f32_e32 v95, v95
	v_exp_f32_e32 v96, v96
	v_exp_f32_e32 v97, v97
	v_add_f32_e32 v183, v82, v183
	v_add_f32_e32 v183, v83, v183
	v_add_f32_e32 v183, v84, v183
	v_add_f32_e32 v183, v85, v183
	v_add_f32_e32 v183, v86, v183
	v_add_f32_e32 v183, v87, v183
	v_add_f32_e32 v183, v88, v183
	v_add_f32_e32 v183, v89, v183
	v_add_f32_e32 v183, v90, v183
	v_add_f32_e32 v183, v91, v183
	v_add_f32_e32 v183, v92, v183
	v_add_f32_e32 v183, v93, v183
	v_add_f32_e32 v183, v94, v183
	v_add_f32_e32 v183, v95, v183
	v_add_f32_e32 v183, v96, v183
	v_add_f32_e32 v183, v97, v183
	v_cvt_pk_bf16_f32 v82, v82, v83
	v_cvt_pk_bf16_f32 v83, v84, v85
	v_cvt_pk_bf16_f32 v84, v86, v87
	v_cvt_pk_bf16_f32 v85, v88, v89
	v_cvt_pk_bf16_f32 v86, v90, v91
	v_cvt_pk_bf16_f32 v87, v92, v93
	v_cvt_pk_bf16_f32 v88, v94, v95
	v_cvt_pk_bf16_f32 v89, v96, v97
	s_nop 0
	s_waitcnt lgkmcnt(4)
	v_mfma_f32_32x32x16_bf16 v[66:81], v[146:149], v[82:85], v[66:81]
	v_mfma_f32_32x32x16_bf16 v[50:65], v[154:157], v[82:85], v[50:65]
	v_exp_f32_e32 v98, v98
	v_exp_f32_e32 v99, v99
	v_exp_f32_e32 v100, v100
	v_exp_f32_e32 v101, v101
	v_exp_f32_e32 v102, v102
	v_mfma_f32_32x32x16_bf16 v[66:81], v[150:153], v[86:89], v[66:81]
	v_exp_f32_e32 v103, v103
	v_exp_f32_e32 v104, v104
	v_exp_f32_e32 v105, v105
	v_exp_f32_e32 v106, v106
	v_exp_f32_e32 v107, v107
	v_mfma_f32_32x32x16_bf16 v[50:65], v[158:161], v[86:89], v[50:65]
	v_exp_f32_e32 v108, v108
	v_exp_f32_e32 v109, v109
	v_exp_f32_e32 v110, v110
	v_exp_f32_e32 v111, v111
	v_exp_f32_e32 v112, v112
	s_waitcnt lgkmcnt(0)
	v_mfma_f32_32x32x16_bf16 v[82:97], v[238:241], v[114:117], v[18:33]
	v_exp_f32_e32 v113, v113
	v_add_f32_e32 v182, v98, v182
	v_add_f32_e32 v182, v99, v182
	v_add_f32_e32 v182, v100, v182
	v_add_f32_e32 v182, v101, v182
	v_mfma_f32_32x32x16_bf16 v[82:97], v[242:245], v[118:121], v[82:97]
	v_add_f32_e32 v182, v102, v182
	v_add_f32_e32 v182, v103, v182
	v_add_f32_e32 v182, v104, v182
	v_add_f32_e32 v182, v105, v182
	v_add_f32_e32 v182, v106, v182
	v_mfma_f32_32x32x16_bf16 v[82:97], v[246:249], v[122:125], v[82:97]
	v_add_f32_e32 v182, v107, v182
	v_add_f32_e32 v182, v108, v182
	v_add_f32_e32 v182, v109, v182
	v_add_f32_e32 v182, v110, v182
	v_add_f32_e32 v182, v111, v182
	v_mfma_f32_32x32x16_bf16 v[82:97], v[204:207], v[126:129], v[82:97]
	v_add_f32_e32 v182, v112, v182
	v_add_f32_e32 v182, v113, v182
	v_cvt_pk_bf16_f32 v98, v98, v99
	v_cvt_pk_bf16_f32 v99, v100, v101
	v_cvt_pk_bf16_f32 v100, v102, v103
	v_cvt_pk_bf16_f32 v101, v104, v105
	v_cvt_pk_bf16_f32 v102, v106, v107
	v_cvt_pk_bf16_f32 v103, v108, v109
	v_cvt_pk_bf16_f32 v104, v110, v111
	v_cvt_pk_bf16_f32 v105, v112, v113
	s_nop 0
	v_mfma_f32_32x32x16_bf16 v[34:49], v[146:149], v[98:101], v[34:49]
	v_mfma_f32_32x32x16_bf16 v[2:17], v[154:157], v[98:101], v[2:17]
	v_exp_f32_e32 v82, v82
	v_exp_f32_e32 v83, v83
	v_exp_f32_e32 v84, v84
	v_exp_f32_e32 v85, v85
	v_exp_f32_e32 v86, v86
	v_mfma_f32_32x32x16_bf16 v[34:49], v[150:153], v[102:105], v[34:49]
	v_exp_f32_e32 v87, v87
	v_exp_f32_e32 v88, v88
	v_exp_f32_e32 v89, v89
	v_exp_f32_e32 v90, v90
	v_exp_f32_e32 v91, v91
	v_mfma_f32_32x32x16_bf16 v[2:17], v[158:161], v[102:105], v[2:17]
	ds_read_b128 v[146:149], v195 offset:64
	ds_read_b128 v[150:153], v195 offset:96
	ds_read_b128 v[154:157], v194 offset:64
	ds_read_b128 v[158:161], v194 offset:96
	v_exp_f32_e32 v92, v92
	v_exp_f32_e32 v93, v93
	v_exp_f32_e32 v94, v94
	v_exp_f32_e32 v95, v95
	v_exp_f32_e32 v96, v96
	v_mfma_f32_32x32x16_bf16 v[98:113], v[238:241], v[130:133], v[18:33]
	v_exp_f32_e32 v97, v97
	v_add_f32_e32 v183, v82, v183
	v_add_f32_e32 v183, v83, v183
	v_add_f32_e32 v183, v84, v183
	v_add_f32_e32 v183, v85, v183
	v_mfma_f32_32x32x16_bf16 v[98:113], v[242:245], v[134:137], v[98:113]
	v_add_f32_e32 v183, v86, v183
	v_add_f32_e32 v183, v87, v183
	v_add_f32_e32 v183, v88, v183
	v_add_f32_e32 v183, v89, v183
	v_add_f32_e32 v183, v90, v183
	v_mfma_f32_32x32x16_bf16 v[98:113], v[246:249], v[138:141], v[98:113]
	v_add_f32_e32 v183, v91, v183
	v_add_f32_e32 v183, v92, v183
	v_add_f32_e32 v183, v93, v183
	v_add_f32_e32 v183, v94, v183
	v_add_f32_e32 v183, v95, v183
	v_mfma_f32_32x32x16_bf16 v[98:113], v[204:207], v[142:145], v[98:113]
	ds_read_b128 v[238:241], v196 offset:9216
	ds_read_b128 v[242:245], v196 offset:9248
	ds_read_b128 v[246:249], v196 offset:9280
	ds_read_b128 v[204:207], v196 offset:9312
	v_add_f32_e32 v183, v96, v183
	v_add_f32_e32 v183, v97, v183
	v_cvt_pk_bf16_f32 v82, v82, v83
	v_cvt_pk_bf16_f32 v83, v84, v85
	v_cvt_pk_bf16_f32 v84, v86, v87
	v_cvt_pk_bf16_f32 v85, v88, v89
	v_cvt_pk_bf16_f32 v86, v90, v91
	v_cvt_pk_bf16_f32 v87, v92, v93
	v_cvt_pk_bf16_f32 v88, v94, v95
	v_cvt_pk_bf16_f32 v89, v96, v97
	s_nop 0
	s_waitcnt lgkmcnt(4)
; __device__ __forceinline__ unsigned cvtpk(float lo, float hi) { f32x2_t v = {lo, hi}; bf16x2_t b = __builtin_convertvector(v, bf16x2_t); return __builtin_bit_cast(unsigned, b); }
; #define LAS __attribute__((address_space(3)))
; __device__ __forceinline__ bool attn_unit(const Ptrs& P, LAS unsigned char* lds, int unit, int tid, int wave, int lane, bool pre, int nxt) {
;     ...
;         for (int kt = 0; kt < 4; ++kt) {
;             if (c == 0 && 32 * kt + 31 < q0) continue;
;             if (c == 2 && 32 * kt > q0 + 63) continue;
;             bf16x8_t kf[4], vf[2][2];
; #pragma unroll
;             for (int ds = 0; ds < 4; ++ds) kf[ds] = *(const LAS bf16x8_t*)(Kl + (32 * kt + r) * AT_KP + (16 * ds + 8 * hh) * 2);
; #pragma unroll
;             for (int db = 0; db < 2; ++db)
; #pragma unroll
;                 for (int s = 0; s < 2; ++s) vf[db][s] = *(const LAS bf16x8_t*)(Vl + (32 * db + r) * AT_VP + (32 * kt + 16 * s + 8 * hh) * 2);
; #pragma unroll
;             for (int cb = 0; cb < 2; ++cb) {
;                 const int dq = 32 * kt - (q0 + 32 * cb);
;                 if ((c == 0 && dq < 0) || (c == 2 && dq > 0)) continue;
;                 const bool diag = (c == 0 || c == 2) && dq == 0;
;                 f32x16 st = MFMA32(kf[0], qf[cb][0], negm);
;                 st = MFMA32(kf[1], qf[cb][1], st); st = MFMA32(kf[2], qf[cb][2], st); st = MFMA32(kf[3], qf[cb][3], st);
;                 float p[16];
; #pragma unroll
;                 for (int i = 0; i < 16; ++i) p[i] = __builtin_amdgcn_exp2f(st[i]);
;                 if (diag) {
;                     const int thr = r - 4 * hh;
; #pragma unroll
;                     for (int i = 0; i < 16; ++i) { const bool vis = c == 0 ? crow(i, 0) >= thr : crow(i, 0) <= thr; p[i] = vis ? p[i] : 0.f; }
;                 }
;                 float s4 = 0.f;
; #pragma unroll
;                 for (int i = 0; i < 16; ++i) s4 += p[i];
;                 rs[cb] += s4;
; #pragma unroll
;                 for (int s = 0; s < 2; ++s) {
;                     u32x4 w; w.x = cvtpk(p[8 * s], p[8 * s + 1]); w.y = cvtpk(p[8 * s + 2], p[8 * s + 3]); w.z = cvtpk(p[8 * s + 4], p[8 * s + 5]); w.w = cvtpk(p[8 * s + 6], p[8 * s + 7]);
;                     const bf16x8_t pb = __builtin_bit_cast(bf16x8_t, w);
;                     o[0][cb] = MFMA32(vf[0][s], pb, o[0][cb]); o[1][cb] = MFMA32(vf[1][s], pb, o[1][cb]);
;                 }
	v_mfma_f32_32x32x16_bf16 v[66:81], v[146:149], v[82:85], v[66:81]
	v_mfma_f32_32x32x16_bf16 v[50:65], v[154:157], v[82:85], v[50:65]
	v_exp_f32_e32 v98, v98
	v_exp_f32_e32 v99, v99
	v_exp_f32_e32 v100, v100
	v_exp_f32_e32 v101, v101
	v_exp_f32_e32 v102, v102
	v_mfma_f32_32x32x16_bf16 v[66:81], v[150:153], v[86:89], v[66:81]
	v_exp_f32_e32 v103, v103
	v_exp_f32_e32 v104, v104
	v_exp_f32_e32 v105, v105
	v_exp_f32_e32 v106, v106
	v_exp_f32_e32 v107, v107
	v_mfma_f32_32x32x16_bf16 v[50:65], v[158:161], v[86:89], v[50:65]
	v_exp_f32_e32 v108, v108
	v_exp_f32_e32 v109, v109
	v_exp_f32_e32 v110, v110
	v_exp_f32_e32 v111, v111
	v_exp_f32_e32 v112, v112
	s_waitcnt lgkmcnt(0)
	v_mfma_f32_32x32x16_bf16 v[82:97], v[238:241], v[114:117], v[18:33]
	v_exp_f32_e32 v113, v113
	v_add_f32_e32 v182, v98, v182
	v_add_f32_e32 v182, v99, v182
	v_add_f32_e32 v182, v100, v182
	v_add_f32_e32 v182, v101, v182
	v_mfma_f32_32x32x16_bf16 v[82:97], v[242:245], v[118:121], v[82:97]
	v_add_f32_e32 v182, v102, v182
	v_add_f32_e32 v182, v103, v182
	v_add_f32_e32 v182, v104, v182
	v_add_f32_e32 v182, v105, v182
	v_add_f32_e32 v182, v106, v182
	v_mfma_f32_32x32x16_bf16 v[82:97], v[246:249], v[122:125], v[82:97]
	v_add_f32_e32 v182, v107, v182
	v_add_f32_e32 v182, v108, v182
	v_add_f32_e32 v182, v109, v182
	v_add_f32_e32 v182, v110, v182
	v_add_f32_e32 v182, v111, v182
	v_mfma_f32_32x32x16_bf16 v[82:97], v[204:207], v[126:129], v[82:97]
	v_add_f32_e32 v182, v112, v182
	v_add_f32_e32 v182, v113, v182
	v_cvt_pk_bf16_f32 v98, v98, v99
	v_cvt_pk_bf16_f32 v99, v100, v101
	v_cvt_pk_bf16_f32 v100, v102, v103
	v_cvt_pk_bf16_f32 v101, v104, v105
	v_cvt_pk_bf16_f32 v102, v106, v107
	v_cvt_pk_bf16_f32 v103, v108, v109
	v_cvt_pk_bf16_f32 v104, v110, v111
	v_cvt_pk_bf16_f32 v105, v112, v113
	s_nop 0
	v_mfma_f32_32x32x16_bf16 v[34:49], v[146:149], v[98:101], v[34:49]
	v_mfma_f32_32x32x16_bf16 v[2:17], v[154:157], v[98:101], v[2:17]
	v_exp_f32_e32 v82, v82
	v_exp_f32_e32 v83, v83
	v_exp_f32_e32 v84, v84
	v_exp_f32_e32 v85, v85
	v_exp_f32_e32 v86, v86
	v_mfma_f32_32x32x16_bf16 v[34:49], v[150:153], v[102:105], v[34:49]
	v_exp_f32_e32 v87, v87
	v_exp_f32_e32 v88, v88
	v_exp_f32_e32 v89, v89
	v_exp_f32_e32 v90, v90
	v_exp_f32_e32 v91, v91
	v_mfma_f32_32x32x16_bf16 v[2:17], v[158:161], v[102:105], v[2:17]
	ds_read_b128 v[146:149], v195 offset:128
	ds_read_b128 v[150:153], v195 offset:160
	ds_read_b128 v[154:157], v194 offset:128
	ds_read_b128 v[158:161], v194 offset:160
	v_exp_f32_e32 v92, v92
	v_exp_f32_e32 v93, v93
	v_exp_f32_e32 v94, v94
	v_exp_f32_e32 v95, v95
	v_exp_f32_e32 v96, v96
	v_mfma_f32_32x32x16_bf16 v[98:113], v[238:241], v[130:133], v[18:33]
	v_exp_f32_e32 v97, v97
	v_add_f32_e32 v183, v82, v183
	v_add_f32_e32 v183, v83, v183
	v_add_f32_e32 v183, v84, v183
	v_add_f32_e32 v183, v85, v183
	v_mfma_f32_32x32x16_bf16 v[98:113], v[242:245], v[134:137], v[98:113]
	v_add_f32_e32 v183, v86, v183
	v_add_f32_e32 v183, v87, v183
	v_add_f32_e32 v183, v88, v183
	v_add_f32_e32 v183, v89, v183
	v_add_f32_e32 v183, v90, v183
	v_mfma_f32_32x32x16_bf16 v[98:113], v[246:249], v[138:141], v[98:113]
	v_add_f32_e32 v183, v91, v183
	v_add_f32_e32 v183, v92, v183
	v_add_f32_e32 v183, v93, v183
	v_add_f32_e32 v183, v94, v183
	v_add_f32_e32 v183, v95, v183
	v_mfma_f32_32x32x16_bf16 v[98:113], v[204:207], v[142:145], v[98:113]
	ds_read_b128 v[238:241], v196 offset:13824
	ds_read_b128 v[242:245], v196 offset:13856
	ds_read_b128 v[246:249], v196 offset:13888
	ds_read_b128 v[204:207], v196 offset:13920
	v_add_f32_e32 v183, v96, v183
	v_add_f32_e32 v183, v97, v183
	v_cvt_pk_bf16_f32 v82, v82, v83
	v_cvt_pk_bf16_f32 v83, v84, v85
	v_cvt_pk_bf16_f32 v84, v86, v87
	v_cvt_pk_bf16_f32 v85, v88, v89
	v_cvt_pk_bf16_f32 v86, v90, v91
	v_cvt_pk_bf16_f32 v87, v92, v93
	v_cvt_pk_bf16_f32 v88, v94, v95
	v_cvt_pk_bf16_f32 v89, v96, v97
	s_nop 0
	s_waitcnt lgkmcnt(4)
	v_mfma_f32_32x32x16_bf16 v[66:81], v[146:149], v[82:85], v[66:81]
	v_mfma_f32_32x32x16_bf16 v[50:65], v[154:157], v[82:85], v[50:65]
	v_exp_f32_e32 v98, v98
	v_exp_f32_e32 v99, v99
	v_exp_f32_e32 v100, v100
	v_exp_f32_e32 v101, v101
	v_exp_f32_e32 v102, v102
	v_mfma_f32_32x32x16_bf16 v[66:81], v[150:153], v[86:89], v[66:81]
	v_exp_f32_e32 v103, v103
	v_exp_f32_e32 v104, v104
	v_exp_f32_e32 v105, v105
	v_exp_f32_e32 v106, v106
	v_exp_f32_e32 v107, v107
	v_mfma_f32_32x32x16_bf16 v[50:65], v[158:161], v[86:89], v[50:65]
	v_exp_f32_e32 v108, v108
	v_exp_f32_e32 v109, v109
	v_exp_f32_e32 v110, v110
	v_exp_f32_e32 v111, v111
	v_exp_f32_e32 v112, v112
	s_waitcnt lgkmcnt(0)
; __device__ __forceinline__ unsigned cvtpk(float lo, float hi) { f32x2_t v = {lo, hi}; bf16x2_t b = __builtin_convertvector(v, bf16x2_t); return __builtin_bit_cast(unsigned, b); }
; __device__ __forceinline__ int crow(int reg, int h) { return (reg & 3) + 8 * (reg >> 2) + 4 * h; }
; #define MFMA32(a, b, c) __builtin_amdgcn_mfma_f32_32x32x16_bf16((a), (b), (c), 0, 0, 0)
; __device__ __forceinline__ bool attn_unit(const Ptrs& P, LAS unsigned char* lds, int unit, int tid, int wave, int lane, bool pre, int nxt) {
;     ...
;             for (int cb = 0; cb < 2; ++cb) {
;                 const int dq = 32 * kt - (q0 + 32 * cb);
;                 if ((c == 0 && dq < 0) || (c == 2 && dq > 0)) continue;
;                 const bool diag = (c == 0 || c == 2) && dq == 0;
;                 f32x16 st = MFMA32(kf[0], qf[cb][0], negm);
;                 st = MFMA32(kf[1], qf[cb][1], st); st = MFMA32(kf[2], qf[cb][2], st); st = MFMA32(kf[3], qf[cb][3], st);
;                 float p[16];
; #pragma unroll
;                 for (int i = 0; i < 16; ++i) p[i] = __builtin_amdgcn_exp2f(st[i]);
;                 if (diag) {
;                     const int thr = r - 4 * hh;
; #pragma unroll
;                     for (int i = 0; i < 16; ++i) { const bool vis = c == 0 ? crow(i, 0) >= thr : crow(i, 0) <= thr; p[i] = vis ? p[i] : 0.f; }
;                 }
;                 float s4 = 0.f;
; #pragma unroll
;                 for (int i = 0; i < 16; ++i) s4 += p[i];
;                 rs[cb] += s4;
; #pragma unroll
;                 for (int s = 0; s < 2; ++s) {
;                     u32x4 w; w.x = cvtpk(p[8 * s], p[8 * s + 1]); w.y = cvtpk(p[8 * s + 2], p[8 * s + 3]); w.z = cvtpk(p[8 * s + 4], p[8 * s + 5]); w.w = cvtpk(p[8 * s + 6], p[8 * s + 7]);
;                     const bf16x8_t pb = __builtin_bit_cast(bf16x8_t, w);
;                     o[0][cb] = MFMA32(vf[0][s], pb, o[0][cb]); o[1][cb] = MFMA32(vf[1][s], pb, o[1][cb]);
;                 }
; __device__ __forceinline__ void mk_p3(const Ptrs& P, LAS unsigned char* lds, int tid, int wave, int lane, int bx, int G, bool dry) {
;     ...
;         { bool pre = false; for (int u = bx; u < NB * 32 * 4; u += G) pre = attn_unit(P, lds, u, tid, wave, lane, pre, u + G < NB * 32 * 4 ? u + G : -1); }
	v_mfma_f32_32x32x16_bf16 v[82:97], v[238:241], v[114:117], v[18:33]
	v_exp_f32_e32 v113, v113
	v_add_f32_e32 v182, v98, v182
	v_add_f32_e32 v182, v99, v182
	v_add_f32_e32 v182, v100, v182
	v_add_f32_e32 v182, v101, v182
	v_mfma_f32_32x32x16_bf16 v[82:97], v[242:245], v[118:121], v[82:97]
	v_add_f32_e32 v182, v102, v182
	v_add_f32_e32 v182, v103, v182
	v_add_f32_e32 v182, v104, v182
	v_add_f32_e32 v182, v105, v182
	v_add_f32_e32 v182, v106, v182
	v_mfma_f32_32x32x16_bf16 v[82:97], v[246:249], v[122:125], v[82:97]
	v_add_f32_e32 v182, v107, v182
	v_add_f32_e32 v182, v108, v182
	v_add_f32_e32 v182, v109, v182
	v_add_f32_e32 v182, v110, v182
	v_add_f32_e32 v182, v111, v182
	v_mfma_f32_32x32x16_bf16 v[82:97], v[204:207], v[126:129], v[82:97]
	v_add_f32_e32 v182, v112, v182
	v_add_f32_e32 v182, v113, v182
	v_cvt_pk_bf16_f32 v98, v98, v99
	v_cvt_pk_bf16_f32 v99, v100, v101
	v_cvt_pk_bf16_f32 v100, v102, v103
	v_cvt_pk_bf16_f32 v101, v104, v105
	v_cvt_pk_bf16_f32 v102, v106, v107
	v_cvt_pk_bf16_f32 v103, v108, v109
	v_cvt_pk_bf16_f32 v104, v110, v111
	v_cvt_pk_bf16_f32 v105, v112, v113
	s_nop 0
	v_mfma_f32_32x32x16_bf16 v[34:49], v[146:149], v[98:101], v[34:49]
	v_mfma_f32_32x32x16_bf16 v[2:17], v[154:157], v[98:101], v[2:17]
	v_exp_f32_e32 v82, v82
	v_exp_f32_e32 v83, v83
	v_exp_f32_e32 v84, v84
	v_exp_f32_e32 v85, v85
	v_exp_f32_e32 v86, v86
	v_mfma_f32_32x32x16_bf16 v[34:49], v[150:153], v[102:105], v[34:49]
	v_exp_f32_e32 v87, v87
	v_exp_f32_e32 v88, v88
	v_exp_f32_e32 v89, v89
	v_exp_f32_e32 v90, v90
	v_exp_f32_e32 v91, v91
	v_mfma_f32_32x32x16_bf16 v[2:17], v[158:161], v[102:105], v[2:17]
	ds_read_b128 v[146:149], v195 offset:192
	ds_read_b128 v[150:153], v195 offset:224
	ds_read_b128 v[154:157], v194 offset:192
	ds_read_b128 v[158:161], v194 offset:224
	v_exp_f32_e32 v92, v92
	v_exp_f32_e32 v93, v93
	v_exp_f32_e32 v94, v94
	v_exp_f32_e32 v95, v95
	v_exp_f32_e32 v96, v96
	v_mfma_f32_32x32x16_bf16 v[98:113], v[238:241], v[130:133], v[18:33]
	v_exp_f32_e32 v97, v97
	v_add_f32_e32 v183, v82, v183
	v_add_f32_e32 v183, v83, v183
	v_add_f32_e32 v183, v84, v183
	v_add_f32_e32 v183, v85, v183
	v_mfma_f32_32x32x16_bf16 v[98:113], v[242:245], v[134:137], v[98:113]
	v_add_f32_e32 v183, v86, v183
	v_add_f32_e32 v183, v87, v183
	v_add_f32_e32 v183, v88, v183
	v_add_f32_e32 v183, v89, v183
	v_add_f32_e32 v183, v90, v183
	v_mfma_f32_32x32x16_bf16 v[98:113], v[246:249], v[138:141], v[98:113]
	v_add_f32_e32 v183, v91, v183
	v_add_f32_e32 v183, v92, v183
	v_add_f32_e32 v183, v93, v183
	v_add_f32_e32 v183, v94, v183
	v_add_f32_e32 v183, v95, v183
	v_mfma_f32_32x32x16_bf16 v[98:113], v[204:207], v[142:145], v[98:113]
	v_add_f32_e32 v183, v96, v183
	v_add_f32_e32 v183, v97, v183
	v_cvt_pk_bf16_f32 v82, v82, v83
	v_cvt_pk_bf16_f32 v83, v84, v85
	v_cvt_pk_bf16_f32 v84, v86, v87
	v_cvt_pk_bf16_f32 v85, v88, v89
	v_cvt_pk_bf16_f32 v86, v90, v91
	v_cvt_pk_bf16_f32 v87, v92, v93
	v_cvt_pk_bf16_f32 v88, v94, v95
	v_cvt_pk_bf16_f32 v89, v96, v97
	s_nop 0
	s_waitcnt lgkmcnt(0)
	v_mfma_f32_32x32x16_bf16 v[66:81], v[146:149], v[82:85], v[66:81]
	v_mfma_f32_32x32x16_bf16 v[50:65], v[154:157], v[82:85], v[50:65]
	v_exp_f32_e32 v98, v98
	v_exp_f32_e32 v99, v99
	v_exp_f32_e32 v100, v100
	v_exp_f32_e32 v101, v101
	v_exp_f32_e32 v102, v102
	v_mfma_f32_32x32x16_bf16 v[66:81], v[150:153], v[86:89], v[66:81]
	v_exp_f32_e32 v103, v103
	v_exp_f32_e32 v104, v104
	v_exp_f32_e32 v105, v105
	v_exp_f32_e32 v106, v106
	v_exp_f32_e32 v107, v107
	v_mfma_f32_32x32x16_bf16 v[50:65], v[158:161], v[86:89], v[50:65]
	v_exp_f32_e32 v108, v108
	v_exp_f32_e32 v109, v109
	v_exp_f32_e32 v110, v110
	v_exp_f32_e32 v111, v111
	v_exp_f32_e32 v112, v112
	v_exp_f32_e32 v113, v113
	v_add_f32_e32 v182, v98, v182
	v_add_f32_e32 v182, v99, v182
	v_add_f32_e32 v182, v100, v182
	v_add_f32_e32 v182, v101, v182
	v_add_f32_e32 v182, v102, v182
	v_add_f32_e32 v182, v103, v182
	v_add_f32_e32 v182, v104, v182
	v_add_f32_e32 v182, v105, v182
	v_add_f32_e32 v182, v106, v182
	v_add_f32_e32 v182, v107, v182
	v_add_f32_e32 v182, v108, v182
	v_add_f32_e32 v182, v109, v182
	v_add_f32_e32 v182, v110, v182
	v_add_f32_e32 v182, v111, v182
	v_add_f32_e32 v182, v112, v182
	v_add_f32_e32 v182, v113, v182
	v_cvt_pk_bf16_f32 v98, v98, v99
	v_cvt_pk_bf16_f32 v99, v100, v101
	v_cvt_pk_bf16_f32 v100, v102, v103
	v_cvt_pk_bf16_f32 v101, v104, v105
	v_cvt_pk_bf16_f32 v102, v106, v107
	v_cvt_pk_bf16_f32 v103, v108, v109
	v_cvt_pk_bf16_f32 v104, v110, v111
	v_cvt_pk_bf16_f32 v105, v112, v113
	s_nop 1
	v_mfma_f32_32x32x16_bf16 v[34:49], v[146:149], v[98:101], v[34:49]
	v_mfma_f32_32x32x16_bf16 v[2:17], v[154:157], v[98:101], v[2:17]
	v_mfma_f32_32x32x16_bf16 v[34:49], v[150:153], v[102:105], v[34:49]
	v_mfma_f32_32x32x16_bf16 v[2:17], v[158:161], v[102:105], v[2:17]
	s_movk_i32 s43, 0x100
	v_readlane_b32 s98, v250, 22
	v_readlane_b32 s99, v250, 23
	s_nop 3
	s_add_i32 s42, s42, s98
	v_writelane_b32 v250, s99, 22
	s_cmpk_gt_i32 s42, 0x1ff
	s_cselect_b64 s[70:71], -1, 0
	s_cmpk_lt_i32 s42, 0x200
	s_cselect_b32 s43, s42, -1
	s_and_b32 s44, s43, 31
	s_cmp_gt_i32 s43, -1
	s_cselect_b64 s[46:47], -1, 0
	v_add_co_u32_e64 v0, s[48:49], s44, -1
	s_and_b64 s[68:69], s[46:47], s[48:49]
	s_waitcnt vmcnt(0) lgkmcnt(0)
	s_barrier
	s_cmp_lt_i32 s43, 0
	s_cbranch_scc1 .Lqpf_skip
	s_and_b32 s98, s43, 31
	s_lshl_b32 s98, s98, 7
	s_add_i32 s98, s98, s33
	s_ashr_i32 s99, s43, 7
	s_lshl_b32 s99, s99, 12
	s_add_i32 s98, s98, s99
	s_lshl_b32 s98, s98, 11
	s_bfe_u32 s99, s43, 0x20005
	s_lshl_b32 s99, s99, 2
	v_readlane_b32 vcc_lo, v251, 40
	s_nop 3
	s_or_b32 s99, s99, vcc_lo
	s_lshl_b32 s99, s99, 7
	s_add_u32 s98, s98, s99
	v_lshl_add_u32 v252, v170, 11, s98
	v_readlane_b32 s98, v251, 63
	v_readlane_b32 s99, v250, 0
	s_nop 7
	global_load_dword v252, v252, s[98:99]

; #define LAS __attribute__((address_space(3)))
; __device__ __forceinline__ void pool_units(const Ptrs& P, LAS unsigned char* lds, int bx, int G, int tid, int wave, int lane) {
;     unsigned char* ws = P.ws; const int NU = (MTOK / 128) * 4;
;     int u = bx; if (u >= NU) return;
;     u32x4 tv[5]; bf16x8_t wa[2][8]; int gcur = -1;
;     const int r = lane & 31, hh = lane >> 5, rb = wave >> 1;
;     ...
;     PL_LOAD(u);
.LBB9_413:
	v_readlane_b32 s97, v251, 39
	v_readlane_b32 s80, v251, 35
	v_readlane_b32 s22, v251, 33
	s_cmpk_gt_i32 s97, 0x1ff
	v_readlane_b32 s83, v251, 38
	v_readlane_b32 s96, v251, 37
	v_readlane_b32 s81, v251, 36
	v_readlane_b32 s23, v251, 34
	s_cbranch_scc1 .LBB9_444
	v_writelane_b32 v250, s94, 20
	v_writelane_b32 v250, s94, 21
	v_mov_b32_e32 v0, 0x24008
	ds_read_b32 v0, v0
	s_waitcnt lgkmcnt(0)
	v_readfirstlane_b32 s98, v0
	s_nop 3
	s_cmp_eq_u32 s98, 1
	s_cbranch_scc0 .Lrm_p
	s_cmpk_lg_i32 s94, 0x100
	s_cbranch_scc1 .Lrm_p
	s_and_b32 s98, s97, 7
	s_lshl_b32 s98, s98, 3
	s_bfe_u32 s99, s97, 0x30003
	s_or_b32 s98, s98, s99
	s_lshr_b32 s99, s97, 6
	s_lshl_b32 s98, s98, 3
	s_or_b32 s97, s98, s99
	s_mov_b32 s98, 4
	s_movk_i32 s99, 0x400
	v_writelane_b32 v250, s98, 20
	v_writelane_b32 v250, s99, 21
.Lrm_p:
	s_ashr_i32 s0, s97, 2
	s_lshl_b32 s1, s0, 7
	s_and_b32 s4, s1, 0xf80
	s_add_u32 s14, s90, 0x7300000
	s_addc_u32 s15, s91, 0
	s_ashr_i32 s1, s0, 31
	s_lshl_b64 s[0:1], s[0:1], 17
	s_add_u32 s0, s14, s0
	s_addc_u32 s1, s15, s1
	s_lshl_b32 s3, s97, 8
	s_and_b32 s3, s3, 0x300
	s_add_u32 s0, s0, s3
	v_lshlrev_b32_e32 v0, 3, v208
	v_mov_b32_e32 v117, 0
	s_addc_u32 s1, s1, 0
	s_add_i32 s4, s4, -8
	v_and_b32_e32 v0, 0x78, v0
	v_lshrrev_b32_e32 v134, 4, v208
	v_mov_b32_e32 v34, v117
	v_mov_b32_e32 v35, v117
	v_lshlrev_b32_e32 v118, 1, v0
	v_mov_b32_e32 v119, v117
	v_add_u32_e32 v0, s4, v134
	s_movk_i32 s3, 0x1000
	v_mov_b32_e32 v32, v117
	v_mov_b32_e32 v33, v117
	v_mov_b64_e32 v[38:39], v[34:35]
	s_movk_i32 s2, 0x300
	v_lshl_add_u64 v[4:5], s[0:1], 0, v[118:119]
	v_cmp_gt_u32_e32 vcc, s3, v0
	v_lshlrev_b32_e32 v0, 10, v134
	v_mov_b64_e32 v[36:37], v[32:33]
	s_and_saveexec_b64 s[0:1], vcc
	s_cbranch_execz .LBB9_416
	v_mov_b32_e32 v1, v117
	v_lshl_add_u64 v[2:3], v[4:5], 0, v[0:1]
	v_add_co_u32_e32 v2, vcc, 0xffffe000, v2
	s_nop 1
	v_addc_co_u32_e32 v3, vcc, -1, v3, vcc
	global_load_dwordx4 v[36:39], v[2:3], off nt

; __device__ __forceinline__ void pool_units(const Ptrs& P, LAS unsigned char* lds, int bx, int G, int tid, int wave, int lane) {
;     ...
;         const int un = u + G; const bool hasn = un < NU;
;         if (hasn) PL_LOAD(un);
.LBB9_426:
	v_readlane_b32 s98, v250, 20
	v_readlane_b32 s99, v250, 21
	s_nop 3
	s_add_i32 s18, s20, s98
	v_writelane_b32 v250, s99, 20
	s_waitcnt lgkmcnt(0)
	s_barrier
	s_cmpk_gt_i32 s18, 0x1ff
	s_cselect_b64 s[10:11], -1, 0
	s_and_b64 vcc, exec, s[10:11]
	s_cbranch_vccnz .LBB9_434
	s_ashr_i32 s2, s18, 2
	s_lshl_b32 s3, s2, 7
	s_and_b32 s6, s3, 0xf80
	s_ashr_i32 s3, s2, 31
	s_lshl_b64 s[2:3], s[2:3], 17
	s_add_u32 s2, s14, s2
	s_addc_u32 s3, s15, s3
	s_lshl_b32 s12, s18, 8
	s_and_b32 s12, s12, 0x300
	s_add_u32 s2, s2, s12
	s_addc_u32 s3, s3, 0
	s_add_i32 s6, s6, -8
	v_mov_b32_e32 v34, v119
	v_mov_b32_e32 v35, v119
	v_add_u32_e32 v2, s6, v134
	v_mov_b32_e32 v32, 0
	v_mov_b32_e32 v33, v119
	v_mov_b64_e32 v[38:39], v[34:35]
	v_lshl_add_u64 v[0:1], s[2:3], 0, v[118:119]
	v_cmp_gt_u32_e32 vcc, s16, v2
	v_mov_b64_e32 v[36:37], v[32:33]
	s_and_saveexec_b64 s[2:3], vcc
	s_cbranch_execz .LBB9_429
	v_lshl_add_u64 v[2:3], v[0:1], 0, v[124:125]
	global_load_dwordx4 v[36:39], v[2:3], off nt

; __device__ __forceinline__ unsigned xb_add(unsigned* p, unsigned v) { return __hip_atomic_fetch_add(p, v, __ATOMIC_RELAXED, __HIP_MEMORY_SCOPE_AGENT); }
; #define SEAM(k) do { if (IN(k) && IN((k) + 1)) GRID_SYNC(); } while (0)
; __device__ __forceinline__ void xcd_barrier(const XcdBarrier& b) {
;     asm volatile("s_waitcnt vmcnt(0)" ::: "memory");
;     __syncthreads();
;     if (threadIdx.x == 0) {
;         unsigned* bar = b.bar;
;         __builtin_amdgcn_s_waitcnt(0);
;         unsigned nloc = b.st[0], nx = b.st[1];
;         if (nloc == 0u) { xcd_barrier_complete(bar, b.x, nloc, nx); b.st[0] = nloc; b.st[1] = nx; }
;         const unsigned old = xb_add(&bar[XB_XSUB(b.x)], 1u);
; __global__ void __launch_bounds__(NTHR, 2) mk_fwd(MkArgs a) {
;     ...
;     SEAM(3);
.LBB9_444:
	v_readlane_b32 s97, v251, 39
	s_cmp_gt_i32 s93, 4
	s_cselect_b64 s[0:1], -1, 0
	s_and_b64 s[2:3], s[22:23], s[0:1]
	s_andn2_b64 vcc, exec, s[2:3]
	s_cbranch_vccnz .LBB9_498
	s_waitcnt vmcnt(0)
	s_waitcnt vmcnt(0) lgkmcnt(0)
	s_barrier
	s_and_saveexec_b64 s[4:5], s[80:81]
	s_cbranch_execz .LBB9_497
	v_mov_b32_e32 v0, 0x24008
	ds_read_b32 v0, v0
	s_waitcnt lgkmcnt(0)
	v_readfirstlane_b32 s98, v0
	s_nop 3
	s_cmp_eq_u32 s98, 1
	s_cbranch_scc0 .Lgb3_orig
	s_cmpk_lg_i32 s94, 0x100
	s_cbranch_scc1 .Lgb3_orig
	s_and_b32 s98, s97, 63
	s_lshl_b32 s98, s98, 2
	s_add_i32 s98, s98, 0x3f00
	v_mov_b32_e32 v0, s98
	v_mov_b32_e32 v1, 1
	global_atomic_add v0, v1, s[90:91]
